# prompt-FoX: -F staged in LDS so the logit-bias fragments load straight into the accumulator init (no per-step sign flips), dead accumulator copies dropped, v_max3 trees without canonicalizing v_max (a
# baseline (speedup 1.0000x reference)
.LBB0_1005:
	s_nop 0
	v_max3_f32 v64, v171, v169, v52
	v_max3_f32 v64, v64, v166, v53
	v_max3_f32 v64, v64, v167, v168
	v_max3_f32 v64, v64, v170, v54
	v_max3_f32 v64, v64, v164, v55
	v_max3_f32 v64, v64, v165, v56
	v_max3_f32 v64, v64, v162, v57
	v_max3_f32 v64, v64, v163, v58
	v_max3_f32 v64, v64, v160, v59
	v_max3_f32 v64, v64, v161, v60
	v_max3_f32 v64, v64, v158, v61
	v_max3_f32 v64, v64, v159, v62
	v_max3_f32 v64, v64, v156, v63
	v_max3_f32 v64, v64, v157, v50
	v_max3_f32 v64, v64, v154, v51
	v_max_f32_e32 v64, v64, v155
	v_and_b32_e32 v182, 64, v218
	v_xor_b32_e32 v65, 32, v218
	v_add_u32_e32 v182, 64, v182
	v_cmp_lt_i32_e32 vcc, v65, v182
	s_nop 1
	v_cndmask_b32_e32 v65, v218, v65, vcc
	v_lshlrev_b32_e32 v65, 2, v65
	ds_bpermute_b32 v65, v65, v64
	s_waitcnt lgkmcnt(0)
	v_max3_f32 v182, v181, v64, v65
	v_sub_f32_e32 v64, v181, v182
	v_exp_f32_e32 v64, v64
	s_nop 0
	v_cmp_neq_f32_e32 vcc, 1.0, v64
	s_cbranch_vccz .LBB0_1007
	v_pk_mul_f32 v[18:19], v[18:19], v[64:65] op_sel_hi:[1,0]
	v_pk_mul_f32 v[16:17], v[16:17], v[64:65] op_sel_hi:[1,0]
	v_pk_mul_f32 v[14:15], v[14:15], v[64:65] op_sel_hi:[1,0]
	v_pk_mul_f32 v[12:13], v[12:13], v[64:65] op_sel_hi:[1,0]
	v_pk_mul_f32 v[10:11], v[10:11], v[64:65] op_sel_hi:[1,0]
	v_pk_mul_f32 v[8:9], v[8:9], v[64:65] op_sel_hi:[1,0]
	v_pk_mul_f32 v[6:7], v[6:7], v[64:65] op_sel_hi:[1,0]
	v_pk_mul_f32 v[4:5], v[4:5], v[64:65] op_sel_hi:[1,0]
	v_pk_mul_f32 v[40:41], v[40:41], v[64:65] op_sel_hi:[1,0]
	v_pk_mul_f32 v[38:39], v[38:39], v[64:65] op_sel_hi:[1,0]
	v_pk_mul_f32 v[36:37], v[36:37], v[64:65] op_sel_hi:[1,0]
	v_pk_mul_f32 v[34:35], v[34:35], v[64:65] op_sel_hi:[1,0]
	v_pk_mul_f32 v[32:33], v[32:33], v[64:65] op_sel_hi:[1,0]
	v_pk_mul_f32 v[30:31], v[30:31], v[64:65] op_sel_hi:[1,0]
	v_pk_mul_f32 v[28:29], v[28:29], v[64:65] op_sel_hi:[1,0]
	v_pk_mul_f32 v[26:27], v[26:27], v[64:65] op_sel_hi:[1,0]

.LBB0_1032:
	s_or_b64 exec, exec, s[12:13]
	v_mul_lo_u32 v6, v6, s82
	v_lshlrev_b32_e32 v3, 2, v188
	v_add_u32_e32 v6, 0, v6
	v_add_u32_e32 v194, v6, v2
	v_add_u32_e32 v195, 0, v3
	s_waitcnt vmcnt(0)
	ds_write_b128 v194, v[162:165]
	ds_write_b128 v194, v[166:169] offset:9216
	s_and_saveexec_b64 s[12:13], s[8:9]
	v_xor_b32_e32 v208, 0x80000000, v1
	ds_write_b32 v195, v208 offset:18432
	s_or_b64 exec, exec, s[12:13]
	v_lshrrev_b32_e32 v7, 2, v188
	v_lshlrev_b32_e32 v189, 2, v8
	v_and_or_b32 v7, v7, 3, v189
	v_lshl_add_u64 v[4:5], s[10:11], 0, v[4:5]
	s_lshl_b32 s10, s53, 5
	s_and_b32 s58, s42, 0xffffffe0
	v_mad_u32_u24 v197, v7, s82, 0
	v_and_b32_e32 v7, 16, v188
	s_and_b32 s10, s10, 0x380
	v_and_b32_e32 v6, 31, v188
	v_and_or_b32 v3, v3, 12, v7
	s_add_i32 s56, s38, 0x100
	s_add_i32 s57, s58, s39
	s_add_i32 s58, s58, s38
	v_or3_b32 v4, v4, s10, v2
	v_mov_b32_e32 v16, v199
	v_mov_b32_e32 v17, v199
	v_mad_u32_u24 v196, v6, s82, 0
	v_lshlrev_b32_e32 v200, 1, v3
	v_or_b32_e32 v201, s57, v6
	v_or_b32_e32 v202, s58, v6
	s_lshr_b32 s59, s56, 6
	v_lshl_add_u64 v[190:191], s[20:21], 0, v[4:5]
	v_mov_b32_e32 v2, v199
	v_mov_b32_e32 v3, v199
	v_mov_b32_e32 v4, v199
	v_mov_b32_e32 v5, v199
	v_mov_b32_e32 v6, v199
	v_mov_b32_e32 v7, v199
	v_mov_b32_e32 v8, v199
	v_mov_b32_e32 v9, v199
	v_mov_b32_e32 v10, v199
	v_mov_b32_e32 v11, v199
	v_mov_b32_e32 v12, v199
	v_mov_b32_e32 v13, v199
	v_mov_b32_e32 v14, v199
	v_mov_b32_e32 v15, v199
	v_mov_b64_e32 v[64:65], v[16:17]
	v_mov_b64_e32 v[32:33], v[16:17]
	v_mov_b64_e32 v[48:49], v[16:17]
	s_add_i32 s55, s39, 0x100
	s_add_i32 s62, s59, -2
	s_or_b32 s63, s57, 31
	s_or_b32 s64, s58, 31
	s_mov_b32 s65, 0
	v_mov_b32_e32 v193, 0
	v_mov_b32_e32 v204, 0xf149f2ca
	v_mov_b32_e32 v205, 0xf149f2ca
	v_mov_b32_e32 v203, 0
	v_mov_b64_e32 v[62:63], v[14:15]
	v_mov_b64_e32 v[60:61], v[12:13]
	v_mov_b64_e32 v[58:59], v[10:11]
	v_mov_b64_e32 v[56:57], v[8:9]
	v_mov_b64_e32 v[54:55], v[6:7]
	v_mov_b64_e32 v[52:53], v[4:5]
	v_mov_b64_e32 v[50:51], v[2:3]
	v_mov_b64_e32 v[30:31], v[14:15]
	v_mov_b64_e32 v[28:29], v[12:13]
	v_mov_b64_e32 v[26:27], v[10:11]
	v_mov_b64_e32 v[24:25], v[8:9]
	v_mov_b64_e32 v[22:23], v[6:7]
	v_mov_b64_e32 v[20:21], v[4:5]
	v_mov_b64_e32 v[18:19], v[2:3]
	v_mov_b64_e32 v[46:47], v[14:15]
	v_mov_b64_e32 v[44:45], v[12:13]
	v_mov_b64_e32 v[42:43], v[10:11]
	v_mov_b64_e32 v[40:41], v[8:9]
	v_mov_b64_e32 v[38:39], v[6:7]
	v_mov_b64_e32 v[36:37], v[4:5]
	v_mov_b64_e32 v[34:35], v[2:3]
	s_mov_b32 s67, 0
	s_waitcnt lgkmcnt(0)
	s_barrier

.LBB0_1039:
	s_cmp_lt_u32 s65, s55
	s_cselect_b64 s[10:11], -1, 0
	s_cmp_le_i32 s65, s63
	s_cselect_b64 s[12:13], -1, 0
	s_and_b64 s[10:11], s[10:11], s[12:13]
	s_cmp_lt_u32 s65, s56
	s_cselect_b64 s[12:13], -1, 0
	s_cmp_le_i32 s65, s64
	s_cselect_b64 s[38:39], -1, 0
	s_and_b64 s[60:61], s[12:13], s[38:39]
	s_or_b64 s[12:13], s[10:11], s[60:61]
	s_andn2_b64 vcc, exec, s[12:13]
	s_cbranch_vccnz .LBB0_1055
	v_add_u32_e32 v98, 0, v198
	ds_read_b128 v[66:69], v98 offset:18432
	ds_read_b128 v[70:73], v98 offset:18464
	ds_read_b128 v[74:77], v98 offset:18496
	ds_read_b128 v[78:81], v98 offset:18528
	ds_read_b128 v[82:85], v98 offset:18560
	ds_read_b128 v[86:89], v98 offset:18592
	ds_read_b128 v[90:93], v98 offset:18624
	ds_read_b128 v[94:97], v98 offset:18656
	v_add_u32_e32 v206, v196, v198
	ds_read_b128 v[182:185], v206
	ds_read_b128 v[178:181], v206 offset:4608
	v_cndmask_b32_e64 v98, 0, 1, s[10:11]
	s_andn2_b64 vcc, exec, s[10:11]
	v_cmp_ne_u32_e64 s[12:13], 1, v98
	s_cbranch_vccz .LBB0_1056
	v_cndmask_b32_e64 v207, 0, 1, s[60:61]
	v_cmp_ne_u32_e64 s[10:11], 1, v207
	s_andn2_b64 vcc, exec, s[60:61]
	s_cbranch_vccz .LBB0_1057

.LBB0_1051:
	s_waitcnt lgkmcnt(0)
	s_nop 3
	s_nop 0
	v_max3_f32 v178, v99, v115, v100
	v_max3_f32 v178, v178, v116, v101
	v_max3_f32 v178, v178, v117, v114
	v_max3_f32 v178, v178, v98, v102
	v_max3_f32 v178, v178, v118, v103
	v_max3_f32 v178, v178, v119, v104
	v_max3_f32 v178, v178, v120, v105
	v_max3_f32 v178, v178, v121, v106
	v_max3_f32 v178, v178, v122, v107
	v_max3_f32 v178, v178, v123, v108
	v_max3_f32 v178, v178, v124, v109
	v_max3_f32 v178, v178, v125, v110
	v_max3_f32 v178, v178, v126, v111
	v_max3_f32 v178, v178, v127, v112
	v_max3_f32 v178, v178, v128, v113
	v_max_f32_e32 v178, v178, v129
	v_and_b32_e32 v180, 64, v218
	v_xor_b32_e32 v179, 32, v218
	v_add_u32_e32 v180, 64, v180
	v_cmp_lt_i32_e32 vcc, v179, v180
	s_nop 1
	v_cndmask_b32_e32 v179, v218, v179, vcc
	v_lshlrev_b32_e32 v179, 2, v179
	ds_bpermute_b32 v179, v179, v178
	s_waitcnt lgkmcnt(0)
	v_max3_f32 v207, v205, v178, v179
	v_sub_f32_e32 v178, v205, v207
	v_exp_f32_e32 v178, v178
	s_nop 0
	v_cmp_neq_f32_e32 vcc, 1.0, v178
	s_cbranch_vccz .LBB0_1053
	v_pk_mul_f32 v[64:65], v[64:65], v[178:179] op_sel_hi:[1,0]
	v_pk_mul_f32 v[62:63], v[62:63], v[178:179] op_sel_hi:[1,0]
	v_pk_mul_f32 v[60:61], v[60:61], v[178:179] op_sel_hi:[1,0]
	v_pk_mul_f32 v[58:59], v[58:59], v[178:179] op_sel_hi:[1,0]
	v_pk_mul_f32 v[56:57], v[56:57], v[178:179] op_sel_hi:[1,0]
	v_pk_mul_f32 v[54:55], v[54:55], v[178:179] op_sel_hi:[1,0]
	v_pk_mul_f32 v[52:53], v[52:53], v[178:179] op_sel_hi:[1,0]
	v_pk_mul_f32 v[50:51], v[50:51], v[178:179] op_sel_hi:[1,0]
	v_pk_mul_f32 v[48:49], v[48:49], v[178:179] op_sel_hi:[1,0]
	v_pk_mul_f32 v[46:47], v[46:47], v[178:179] op_sel_hi:[1,0]
	v_pk_mul_f32 v[44:45], v[44:45], v[178:179] op_sel_hi:[1,0]
	v_pk_mul_f32 v[42:43], v[42:43], v[178:179] op_sel_hi:[1,0]
	v_pk_mul_f32 v[40:41], v[40:41], v[178:179] op_sel_hi:[1,0]
	v_pk_mul_f32 v[38:39], v[38:39], v[178:179] op_sel_hi:[1,0]
	v_pk_mul_f32 v[36:37], v[36:37], v[178:179] op_sel_hi:[1,0]
	v_pk_mul_f32 v[34:35], v[34:35], v[178:179] op_sel_hi:[1,0]

.LBB0_1067:
	s_nop 3
	s_nop 0
	v_max3_f32 v114, v83, v67, v84
	v_max3_f32 v114, v114, v68, v85
	v_max3_f32 v114, v114, v69, v66
	v_max3_f32 v114, v114, v82, v86
	v_max3_f32 v114, v114, v70, v87
	v_max3_f32 v114, v114, v71, v88
	v_max3_f32 v114, v114, v72, v89
	v_max3_f32 v114, v114, v73, v90
	v_max3_f32 v114, v114, v74, v91
	v_max3_f32 v114, v114, v75, v92
	v_max3_f32 v114, v114, v76, v93
	v_max3_f32 v114, v114, v77, v94
	v_max3_f32 v114, v114, v78, v95
	v_max3_f32 v114, v114, v79, v96
	v_max3_f32 v114, v114, v80, v97
	v_max_f32_e32 v114, v114, v81
	v_and_b32_e32 v116, 64, v218
	v_xor_b32_e32 v115, 32, v218
	v_add_u32_e32 v116, 64, v116
	v_cmp_lt_i32_e32 vcc, v115, v116
	s_nop 1
	v_cndmask_b32_e32 v115, v218, v115, vcc
	v_lshlrev_b32_e32 v115, 2, v115
	ds_bpermute_b32 v115, v115, v114
	s_waitcnt lgkmcnt(0)
	v_max3_f32 v206, v204, v114, v115
	v_sub_f32_e32 v114, v204, v206
	v_exp_f32_e32 v114, v114
	s_nop 0
	v_cmp_neq_f32_e32 vcc, 1.0, v114
	s_cbranch_vccz .LBB0_1069
	v_pk_mul_f32 v[16:17], v[16:17], v[114:115] op_sel_hi:[1,0]
	v_pk_mul_f32 v[14:15], v[14:15], v[114:115] op_sel_hi:[1,0]
	v_pk_mul_f32 v[12:13], v[12:13], v[114:115] op_sel_hi:[1,0]
	v_pk_mul_f32 v[10:11], v[10:11], v[114:115] op_sel_hi:[1,0]
	v_pk_mul_f32 v[8:9], v[8:9], v[114:115] op_sel_hi:[1,0]
	v_pk_mul_f32 v[6:7], v[6:7], v[114:115] op_sel_hi:[1,0]
	v_pk_mul_f32 v[4:5], v[4:5], v[114:115] op_sel_hi:[1,0]
	v_pk_mul_f32 v[2:3], v[2:3], v[114:115] op_sel_hi:[1,0]
	v_pk_mul_f32 v[32:33], v[32:33], v[114:115] op_sel_hi:[1,0]
	v_pk_mul_f32 v[30:31], v[30:31], v[114:115] op_sel_hi:[1,0]
	v_pk_mul_f32 v[28:29], v[28:29], v[114:115] op_sel_hi:[1,0]
	v_pk_mul_f32 v[26:27], v[26:27], v[114:115] op_sel_hi:[1,0]
	v_pk_mul_f32 v[24:25], v[24:25], v[114:115] op_sel_hi:[1,0]
	v_pk_mul_f32 v[22:23], v[22:23], v[114:115] op_sel_hi:[1,0]
	v_pk_mul_f32 v[20:21], v[20:21], v[114:115] op_sel_hi:[1,0]
	v_pk_mul_f32 v[18:19], v[18:19], v[114:115] op_sel_hi:[1,0]

.LBB0_1086:
	s_add_i32 s12, s67, 1
	s_cmp_lt_u32 s12, s59
	s_cselect_b64 s[10:11], -1, 0
	s_cmp_ge_u32 s12, s59
	s_cbranch_scc1 .LBB0_1090
	s_waitcnt vmcnt(1)
	ds_write_b128 v194, v[170:173] offset:32768
	s_waitcnt vmcnt(0)
	ds_write_b128 v194, v[174:177] offset:41984
	s_and_saveexec_b64 s[12:13], s[8:9]
	v_xor_b32_e32 v208, 0x80000000, v192
	ds_write_b32 v195, v208 offset:51200
	s_or_b64 exec, exec, s[12:13]

.LBB0_1095:
	s_add_i32 s38, s65, 64
	s_cmp_lt_u32 s38, s55
	s_cselect_b64 s[10:11], -1, 0
	s_cmp_le_i32 s38, s63
	s_cselect_b64 s[12:13], -1, 0
	s_and_b64 s[10:11], s[10:11], s[12:13]
	s_cmp_lt_u32 s38, s56
	s_cselect_b64 s[12:13], -1, 0
	s_cmp_le_i32 s38, s64
	s_cselect_b64 s[38:39], -1, 0
	s_and_b64 s[60:61], s[12:13], s[38:39]
	s_or_b64 s[12:13], s[10:11], s[60:61]
	s_andn2_b64 vcc, exec, s[12:13]
	s_cbranch_vccnz .LBB0_1112
	v_add_u32_e32 v98, 0, v198
	ds_read_b128 v[66:69], v98 offset:51200
	ds_read_b128 v[70:73], v98 offset:51232
	ds_read_b128 v[74:77], v98 offset:51264
	ds_read_b128 v[78:81], v98 offset:51296
	ds_read_b128 v[82:85], v98 offset:51328
	ds_read_b128 v[86:89], v98 offset:51360
	ds_read_b128 v[90:93], v98 offset:51392
	ds_read_b128 v[94:97], v98 offset:51424
	v_add_u32_e32 v204, v196, v198
	ds_read_b128 v[182:185], v204 offset:32768
	ds_read_b128 v[178:181], v204 offset:37376
	v_cndmask_b32_e64 v98, 0, 1, s[10:11]
	s_andn2_b64 vcc, exec, s[10:11]
	v_cmp_ne_u32_e64 s[12:13], 1, v98
	s_cbranch_vccz .LBB0_1113
	v_cndmask_b32_e64 v205, 0, 1, s[60:61]
	v_cmp_ne_u32_e64 s[10:11], 1, v205
	s_andn2_b64 vcc, exec, s[60:61]
	s_cbranch_vccz .LBB0_1114

.LBB0_1107:
	s_waitcnt lgkmcnt(0)
	s_nop 3
	s_nop 0
	v_max3_f32 v178, v99, v115, v100
	v_max3_f32 v178, v178, v116, v101
	v_max3_f32 v178, v178, v117, v114
	v_max3_f32 v178, v178, v98, v102
	v_max3_f32 v178, v178, v118, v103
	v_max3_f32 v178, v178, v119, v104
	v_max3_f32 v178, v178, v120, v105
	v_max3_f32 v178, v178, v121, v106
	v_max3_f32 v178, v178, v122, v107
	v_max3_f32 v178, v178, v123, v108
	v_max3_f32 v178, v178, v124, v109
	v_max3_f32 v178, v178, v125, v110
	v_max3_f32 v178, v178, v126, v111
	v_max3_f32 v178, v178, v127, v112
	v_max3_f32 v178, v178, v128, v113
	v_max_f32_e32 v178, v178, v129
	v_and_b32_e32 v180, 64, v218
	v_xor_b32_e32 v179, 32, v218
	v_add_u32_e32 v180, 64, v180
	v_cmp_lt_i32_e32 vcc, v179, v180
	s_nop 1
	v_cndmask_b32_e32 v179, v218, v179, vcc
	v_lshlrev_b32_e32 v179, 2, v179
	ds_bpermute_b32 v179, v179, v178
	s_waitcnt lgkmcnt(0)
	v_max3_f32 v205, v207, v178, v179
	v_sub_f32_e32 v178, v207, v205
	v_exp_f32_e32 v178, v178
	s_nop 0
	v_cmp_neq_f32_e32 vcc, 1.0, v178
	s_cbranch_vccz .LBB0_1109
	v_pk_mul_f32 v[64:65], v[64:65], v[178:179] op_sel_hi:[1,0]
	v_pk_mul_f32 v[62:63], v[62:63], v[178:179] op_sel_hi:[1,0]
	v_pk_mul_f32 v[60:61], v[60:61], v[178:179] op_sel_hi:[1,0]
	v_pk_mul_f32 v[58:59], v[58:59], v[178:179] op_sel_hi:[1,0]
	v_pk_mul_f32 v[56:57], v[56:57], v[178:179] op_sel_hi:[1,0]
	v_pk_mul_f32 v[54:55], v[54:55], v[178:179] op_sel_hi:[1,0]
	v_pk_mul_f32 v[52:53], v[52:53], v[178:179] op_sel_hi:[1,0]
	v_pk_mul_f32 v[50:51], v[50:51], v[178:179] op_sel_hi:[1,0]
	v_pk_mul_f32 v[48:49], v[48:49], v[178:179] op_sel_hi:[1,0]
	v_pk_mul_f32 v[46:47], v[46:47], v[178:179] op_sel_hi:[1,0]
	v_pk_mul_f32 v[44:45], v[44:45], v[178:179] op_sel_hi:[1,0]
	v_pk_mul_f32 v[42:43], v[42:43], v[178:179] op_sel_hi:[1,0]
	v_pk_mul_f32 v[40:41], v[40:41], v[178:179] op_sel_hi:[1,0]
	v_pk_mul_f32 v[38:39], v[38:39], v[178:179] op_sel_hi:[1,0]
	v_pk_mul_f32 v[36:37], v[36:37], v[178:179] op_sel_hi:[1,0]
	v_pk_mul_f32 v[34:35], v[34:35], v[178:179] op_sel_hi:[1,0]

.LBB0_1124:
	s_nop 3
	s_nop 0
	v_max3_f32 v114, v83, v67, v84
	v_max3_f32 v114, v114, v68, v85
	v_max3_f32 v114, v114, v69, v66
	v_max3_f32 v114, v114, v82, v86
	v_max3_f32 v114, v114, v70, v87
	v_max3_f32 v114, v114, v71, v88
	v_max3_f32 v114, v114, v72, v89
	v_max3_f32 v114, v114, v73, v90
	v_max3_f32 v114, v114, v74, v91
	v_max3_f32 v114, v114, v75, v92
	v_max3_f32 v114, v114, v76, v93
	v_max3_f32 v114, v114, v77, v94
	v_max3_f32 v114, v114, v78, v95
	v_max3_f32 v114, v114, v79, v96
	v_max3_f32 v114, v114, v80, v97
	v_max_f32_e32 v114, v114, v81
	v_and_b32_e32 v116, 64, v218
	v_xor_b32_e32 v115, 32, v218
	v_add_u32_e32 v116, 64, v116
	v_cmp_lt_i32_e32 vcc, v115, v116
	s_nop 1
	v_cndmask_b32_e32 v115, v218, v115, vcc
	v_lshlrev_b32_e32 v115, 2, v115
	ds_bpermute_b32 v115, v115, v114
	s_waitcnt lgkmcnt(0)
	v_max3_f32 v204, v206, v114, v115
	v_sub_f32_e32 v114, v206, v204
	v_exp_f32_e32 v114, v114
	s_nop 0
	v_cmp_neq_f32_e32 vcc, 1.0, v114
	s_cbranch_vccz .LBB0_1126
	v_pk_mul_f32 v[16:17], v[16:17], v[114:115] op_sel_hi:[1,0]
	v_pk_mul_f32 v[14:15], v[14:15], v[114:115] op_sel_hi:[1,0]
	v_pk_mul_f32 v[12:13], v[12:13], v[114:115] op_sel_hi:[1,0]
	v_pk_mul_f32 v[10:11], v[10:11], v[114:115] op_sel_hi:[1,0]
	v_pk_mul_f32 v[8:9], v[8:9], v[114:115] op_sel_hi:[1,0]
	v_pk_mul_f32 v[6:7], v[6:7], v[114:115] op_sel_hi:[1,0]
	v_pk_mul_f32 v[4:5], v[4:5], v[114:115] op_sel_hi:[1,0]
	v_pk_mul_f32 v[2:3], v[2:3], v[114:115] op_sel_hi:[1,0]
	v_pk_mul_f32 v[32:33], v[32:33], v[114:115] op_sel_hi:[1,0]
	v_pk_mul_f32 v[30:31], v[30:31], v[114:115] op_sel_hi:[1,0]
	v_pk_mul_f32 v[28:29], v[28:29], v[114:115] op_sel_hi:[1,0]
	v_pk_mul_f32 v[26:27], v[26:27], v[114:115] op_sel_hi:[1,0]
	v_pk_mul_f32 v[24:25], v[24:25], v[114:115] op_sel_hi:[1,0]
	v_pk_mul_f32 v[22:23], v[22:23], v[114:115] op_sel_hi:[1,0]
	v_pk_mul_f32 v[20:21], v[20:21], v[114:115] op_sel_hi:[1,0]
	v_pk_mul_f32 v[18:19], v[18:19], v[114:115] op_sel_hi:[1,0]

.LBB0_1142:
	s_waitcnt vmcnt(1)
	ds_write_b128 v194, v[162:165]
	s_waitcnt vmcnt(0)
	ds_write_b128 v194, v[166:169] offset:9216
	s_and_saveexec_b64 s[10:11], s[8:9]
	v_xor_b32_e32 v208, 0x80000000, v1
	ds_write_b32 v195, v208 offset:18432
	s_or_b64 exec, exec, s[10:11]
